# grid barrier: L1 invalidate (agent acquire) issued by waiting blocks at arrival and by the XCD leader after publishing the generation, off the release path
# speedup vs baseline: 1.0165x; 1.0128x over previous
.LBB0_927:
	s_or_b64 exec, exec, s[2:3]
	v_cvt_f32_u32_e32 v5, v3
	s_waitcnt vmcnt(0)
	v_readfirstlane_b32 s2, v4
	v_sub_u32_e32 v4, 0, v3
	v_rcp_iflag_f32_e32 v5, v5
	v_add_u32_e32 v6, s2, v0
	v_mul_f32_e32 v5, 0x4f7ffffe, v5
	v_cvt_u32_f32_e32 v5, v5
	v_mul_lo_u32 v0, v4, v5
	v_mul_hi_u32 v0, v5, v0
	v_add_u32_e32 v0, v5, v0
	v_mul_hi_u32 v0, v6, v0
	v_mul_lo_u32 v4, v0, v3
	v_sub_u32_e32 v4, v6, v4
	v_add_u32_e32 v5, 1, v0
	v_cmp_ge_u32_e32 vcc, v4, v3
	s_nop 1
	v_cndmask_b32_e32 v0, v0, v5, vcc
	v_sub_u32_e32 v5, v4, v3
	v_cndmask_b32_e32 v4, v4, v5, vcc
	v_add_u32_e32 v5, 1, v0
	v_cmp_ge_u32_e32 vcc, v4, v3
	v_add_u32_e32 v4, 1, v6
	s_nop 0
	v_cndmask_b32_e32 v0, v0, v5, vcc
	v_mul_lo_u32 v5, v3, v0
	v_add_u32_e32 v3, v5, v3
	v_cmp_ne_u32_e32 vcc, v4, v3
	s_and_saveexec_b64 s[2:3], vcc
	s_xor_b64 s[2:3], exec, s[2:3]
	s_cbranch_execz .LBB0_941
	v_readlane_b32 s4, v244, 4
	v_readlane_b32 s5, v244, 5
	s_waitcnt lgkmcnt(0)
	buffer_inv sc1
	s_nop 3
	global_load_dword v2, v1, s[4:5] sc1
	s_waitcnt vmcnt(0)
	v_cmp_eq_u32_e32 vcc, v2, v0
	s_and_saveexec_b64 s[4:5], vcc
	s_cbranch_execz .LBB0_940
	s_mov_b32 s8, 1
	s_mov_b64 s[6:7], 0
	s_branch .LBB0_931

.LBB0_940:
	s_or_b64 exec, exec, s[4:5]
	s_waitcnt vmcnt(0)
	s_nop 0
	s_waitcnt vmcnt(0)

.LBB0_958:
	s_or_b64 exec, exec, s[2:3]
	s_mov_b64 s[2:3], exec
	v_mbcnt_lo_u32_b32 v0, s2, 0
	v_mbcnt_hi_u32_b32 v0, s3, v0
	v_cmp_eq_u32_e32 vcc, 0, v0
	s_waitcnt vmcnt(0)
	s_nop 0
	s_and_saveexec_b64 s[4:5], vcc
	s_cbranch_execnz .LBB0_959
	s_getpc_b64 s[98:99]

.LBB0_959:
	s_bcnt1_i32_b64 s2, s[2:3]
	v_mov_b32_e32 v0, s2
	v_readlane_b32 s2, v244, 4
	v_readlane_b32 s3, v244, 5
	s_nop 4
	global_atomic_add v1, v0, s[2:3]
	buffer_inv sc1
	s_getpc_b64 s[98:99]
